# attnA: one barrier in the middle of each step, K fragments of the next tile prefetched into registers in the second half, V DMA lags K by one tile
# baseline (speedup 1.0000x reference)
; #define LAS __attribute__((address_space(3)))
; #define A_WAITBAR(ahead) do { if ((ahead) >= 2) asm volatile("s_waitcnt vmcnt(8)" ::: "memory"); else if ((ahead) == 1) asm volatile("s_waitcnt vmcnt(4)" ::: "memory"); else asm volatile("s_waitcnt vmcnt(0)" ::: "memory"); \
;         __builtin_amdgcn_s_barrier(); asm volatile("" ::: "memory"); } while (0)
; __device__ __forceinline__ void attnA_unit(const P2Ctx& C, int b, int h, int qb) {
;     LAS unsigned char* lds = C.lds; const int lane = C.lane, wid = C.wid, pf = C.pf;
;     const int comp = wid >> 2, qs = wid & 3, r32 = lane & 31, hi = lane >> 5;
;     const int q0 = qb * 128, trow0 = b * SEQ;
;     const int qpos = q0 + qs * 32 + r32; const size_t qrow = (size_t)(trow0 + qpos);
;     const int qcw = (q0 + qs * 32) >> 6, ntw = qcw + 1, NT = 2 * qb + 2;
;     const LAS float* lut = (const LAS float*)(lds + LUT_OFF) + h * 256;
;     const float lam = *(const LAS float*)(lds + LAM_OFF);
;     bf16x8 qf[4];
; #pragma unroll
;     for (int ds = 0; ds < 4; ++ds) qf[ds] = *(const bf16x8*)(C.Q + qrow * DM + h * 128 + comp * 64 + ds * 16 + hi * 8);
;     const int kkey = 8 * wid + (lane >> 3), kchs = (lane & 7) ^ ((kkey >> 1) & 7);
;     const bf16_t* ksrc = C.Kb + ((size_t)trow0 + kkey) * DM + h * 128 + kchs * 8;
;     const bf16_t* vsrc[2];
; #pragma unroll
;     for (int i = 0; i < 2; ++i) { const int p = 2 * wid + i, kg = p >> 1, cbv = 2 * (p & 1) + (lane >> 5), vkey = kg * 8 + ((lane >> 2) & 7), vch = cbv * 4 + (lane & 3);
;         vsrc[i] = C.Vb + ((size_t)trow0 + vkey) * DM + h * 128 + vch * 8; }
;     ...
;     A_DMA(0); A_DMA(1);
;     A_WAITBAR(1);
.LBB0_572:
	s_andn2_b64 vcc, exec, s[6:7]
	s_cbranch_vccnz .LBB0_614
	s_sub_i32 s6, s37, 32
	s_lshr_b32 s11, s6, 4
	s_and_b32 s6, s6, 15
	s_sub_i32 s10, 15, s6
	s_lshr_b32 s8, s83, 2
	s_and_b32 s9, s83, 3
	s_lshl_b32 s12, s10, 1
	s_add_i32 s12, s12, 2
	s_lshr_b32 s6, s9, 1
	s_lshl_b32 s13, s10, 1
	s_add_i32 s13, s13, s6
	s_add_i32 s13, s13, 1
	s_lshl_b32 s22, s83, 10
	s_lshl_b32 s23, s83, 11
	s_add_i32 s23, s23, 0x4000
	s_lshl_b32 s6, s10, 7
	s_lshl_b32 s7, s9, 5
	s_add_i32 s15, s6, s7
	s_add_i32 s26, s15, 0xffffff01
	s_mov_b32 s25, 0
	v_and_b32_e32 v100, 31, v219
	v_lshrrev_b32_e32 v101, 5, v219
	s_load_dwordx2 s[20:21], s[62:63], 0x80
	v_lshlrev_b32_e32 v107, 4, v196
	s_waitcnt lgkmcnt(0)
	v_cmp_gt_u32_e32 vcc, 32, v196
	s_and_saveexec_b64 s[6:7], vcc
	global_load_dwordx4 v[108:111], v107, s[20:21]
	s_or_b64 exec, exec, s[6:7]
	s_lshl_b32 s6, s11, 11
	s_add_i32 s6, s6, s15
	s_lshl_b32 s6, s6, 11
	s_lshl_b32 s7, s81, 1
	s_add_i32 s6, s6, s7
	s_lshl_b32 s7, s8, 7
	s_add_i32 s6, s6, s7
	s_add_u32 s20, s76, s6
	s_addc_u32 s21, s77, 0
	v_lshlrev_b32_e32 v102, 11, v100
	v_lshl_add_u32 v102, v101, 4, v102
	global_load_dwordx4 v[164:167], v102, s[20:21]
	global_load_dwordx4 v[168:171], v102, s[20:21] offset:32
	global_load_dwordx4 v[172:175], v102, s[20:21] offset:64
	global_load_dwordx4 v[176:179], v102, s[20:21] offset:96
	s_lshl_b32 s6, s11, 22
	s_lshl_b32 s7, s81, 1
	s_add_i32 s6, s6, s7
	s_add_u32 s16, s72, s6
	s_addc_u32 s17, s73, 0
	s_add_u32 s18, s74, s6
	s_addc_u32 s19, s75, 0
	s_mov_b32 s24, 0
	v_lshrrev_b32_e32 v103, 3, v219
	s_lshl_b32 s6, s83, 3
	v_add_u32_e32 v103, s6, v103
	v_bfe_u32 v104, v103, 1, 3
	v_and_b32_e32 v105, 7, v219
	v_xor_b32_e32 v104, v104, v105
	v_lshlrev_b32_e32 v104, 4, v104
	v_lshl_add_u32 v197, v103, 11, v104
	v_bfe_u32 v103, v219, 2, 3
	v_add_u32_e32 v103, s6, v103
	v_and_b32_e32 v104, 3, v219
	v_lshlrev_b32_e32 v104, 4, v104
	v_lshl_add_u32 v104, v101, 6, v104
	v_lshl_add_u32 v198, v103, 11, v104
	s_and_b32 s6, s24, 3
	s_lshl_b32 s6, s6, 15
	s_add_i32 s7, s6, s22
	s_mov_b32 m0, s7
	s_add_u32 s20, s16, 0x80
	s_addc_u32 s21, s17, 0
	s_nop 0
	global_load_lds_dwordx4 v197, s[16:17]
	s_add_i32 m0, s7, 0x2000
	s_add_u32 s16, s16, 0x20000
	s_addc_u32 s17, s17, 0
	s_nop 0
	global_load_lds_dwordx4 v197, s[20:21]
	s_add_i32 s24, s24, 1
	s_and_b32 s6, s24, 3
	s_lshl_b32 s6, s6, 15
	s_add_i32 s7, s6, s22
	s_mov_b32 m0, s7
	s_add_u32 s20, s16, 0x80
	s_addc_u32 s21, s17, 0
	s_nop 0
	global_load_lds_dwordx4 v197, s[16:17]
	s_add_i32 m0, s7, 0x2000
	s_add_u32 s16, s16, 0x20000
	s_addc_u32 s17, s17, 0
	s_nop 0
	global_load_lds_dwordx4 v197, s[20:21]
	s_add_i32 s6, s24, -1
	s_and_b32 s6, s6, 3
	s_lshl_b32 s6, s6, 15
	s_add_i32 s29, s6, s23
	s_mov_b32 m0, s29
	s_add_u32 s20, s18, 0x80
	s_addc_u32 s21, s19, 0
	s_nop 0
	global_load_lds_dwordx4 v198, s[18:19]
	s_add_i32 m0, s29, 0x400
	s_add_u32 s18, s18, 0x20000
	s_addc_u32 s19, s19, 0
	s_nop 0
	global_load_lds_dwordx4 v198, s[20:21]
	s_add_i32 s24, s24, 1
	v_bfe_u32 v103, v100, 1, 3
	v_lshlrev_b32_e32 v104, 7, v100
	s_lshl_b32 s6, s8, 13
	v_add_u32_e32 v104, s6, v104
	v_or_b32_e32 v105, 0, v101
	v_xor_b32_e32 v105, v105, v103
	v_lshl_add_u32 v200, v105, 4, v104
	v_or_b32_e32 v105, 2, v101
	v_xor_b32_e32 v105, v105, v103
	v_lshl_add_u32 v201, v105, 4, v104
	v_or_b32_e32 v105, 4, v101
	v_xor_b32_e32 v105, v105, v103
	v_lshl_add_u32 v202, v105, 4, v104
	v_or_b32_e32 v105, 6, v101
	v_xor_b32_e32 v105, v105, v103
	v_lshl_add_u32 v203, v105, 4, v104
	v_bfe_u32 v103, v219, 2, 2
	v_lshl_add_u32 v103, v101, 2, v103
	v_lshlrev_b32_e32 v103, 6, v103
	v_bfe_u32 v104, v219, 4, 1
	v_lshl_add_u32 v103, v104, 5, v103
	v_and_b32_e32 v104, 3, v219
	v_lshl_add_u32 v103, v104, 3, v103
	v_add_u32_e32 v204, 0x4000, v103
	s_sub_i32 s6, 0x120, s15
	s_lshl_b32 s6, s6, 2
	s_add_i32 s6, s6, 0x22400
	v_lshlrev_b32_e32 v103, 4, v101
	v_lshlrev_b32_e32 v104, 2, v100
	v_sub_u32_e32 v103, v103, v104
	v_add_u32_e32 v236, s6, v103
	v_cmp_gt_u32_e32 vcc, 0x160, v196
	s_and_saveexec_b64 s[6:7], vcc
	s_cbranch_execz .LaA_padskip_1
	v_subrev_u32_e32 v103, 0x60, v196
	v_max_i32_e32 v104, 0, v103
	v_lshl_add_u32 v104, v104, 2, s42
	ds_read_b32 v105, v104
	v_cmp_gt_i32_e32 vcc, 0, v103
	v_mov_b32_e32 v106, 0x22400
	v_lshl_add_u32 v104, v196, 2, v106
	s_waitcnt lgkmcnt(0)
	v_cndmask_b32_e64 v105, v105, 0, vcc
	ds_write_b32 v104, v105

; #define A_WAITBAR(ahead) do { if ((ahead) >= 2) asm volatile("s_waitcnt vmcnt(8)" ::: "memory"); else if ((ahead) == 1) asm volatile("s_waitcnt vmcnt(4)" ::: "memory"); else asm volatile("s_waitcnt vmcnt(0)" ::: "memory"); \
;         __builtin_amdgcn_s_barrier(); asm volatile("" ::: "memory"); } while (0)
; #define A_MAX() \
;         float mx = fmaxf(s[0][0], s[1][0]); \
;         _Pragma("unroll") for (int r = 1; r < 16; ++r) mx = fmaxf(fmaxf(mx, s[0][r]), s[1][r]); \
;         mx = fmaxf(mx, __shfl_xor(mx, 32));
; __device__ __forceinline__ void attnA_unit(const P2Ctx& C, int b, int h, int qb) {
;     ...
;     A_DMA(0); A_DMA(1);
;     A_WAITBAR(1);
;     { if (2 < NT && !(pf & 16)) A_DMA(2);
;       A_QK(0)
;       if (!(pf & 4)) {
;       A_MAX()
;       mhat = mx;
; #pragma unroll
;       for (int kb2 = 0; kb2 < 2; ++kb2)
; #pragma unroll
;           for (int r = 0; r < 16; ++r) s[kb2][r] -= mx;
.LaA_far0_5:
	v_max_f32_e32 v242, v68, v69
	v_max_f32_e32 v243, v84, v85
	v_max3_f32 v242, v242, v70, v71
	v_max3_f32 v243, v243, v86, v87
	v_max3_f32 v242, v242, v72, v73
	v_max3_f32 v243, v243, v88, v89
	v_max3_f32 v242, v242, v74, v75
	v_max3_f32 v243, v243, v90, v91
	v_max3_f32 v242, v242, v76, v77
	v_max3_f32 v243, v243, v92, v93
	v_max3_f32 v242, v242, v78, v79
	v_max3_f32 v243, v243, v94, v95
	v_max3_f32 v242, v242, v80, v81
	v_max3_f32 v243, v243, v96, v97
	v_max3_f32 v242, v242, v82, v83
	v_max3_f32 v243, v243, v98, v99
	v_max_f32_e32 v242, v242, v243
	v_mov_b32_e32 v243, v242
	s_nop 1
	v_permlane32_swap_b32 v243, v242
	v_max_f32_e32 v247, v243, v242
	v_mov_b32_e32 v240, v247
	v_sub_f32_e32 v68, v68, v247
	v_sub_f32_e32 v69, v69, v247
	v_sub_f32_e32 v70, v70, v247
	v_sub_f32_e32 v71, v71, v247
	v_sub_f32_e32 v72, v72, v247
	v_sub_f32_e32 v73, v73, v247
	v_sub_f32_e32 v74, v74, v247
	v_sub_f32_e32 v75, v75, v247
	v_sub_f32_e32 v76, v76, v247
	v_sub_f32_e32 v77, v77, v247
	v_sub_f32_e32 v78, v78, v247
	v_sub_f32_e32 v79, v79, v247
	v_sub_f32_e32 v80, v80, v247
	v_sub_f32_e32 v81, v81, v247
	v_sub_f32_e32 v82, v82, v247
	v_sub_f32_e32 v83, v83, v247
	v_sub_f32_e32 v84, v84, v247
	v_sub_f32_e32 v85, v85, v247
	v_sub_f32_e32 v86, v86, v247
	v_sub_f32_e32 v87, v87, v247
	v_sub_f32_e32 v88, v88, v247
	v_sub_f32_e32 v89, v89, v247
	v_sub_f32_e32 v90, v90, v247
	v_sub_f32_e32 v91, v91, v247
	v_sub_f32_e32 v92, v92, v247
	v_sub_f32_e32 v93, v93, v247
	v_sub_f32_e32 v94, v94, v247
	v_sub_f32_e32 v95, v95, v247
	v_sub_f32_e32 v96, v96, v247
	v_sub_f32_e32 v97, v97, v247
	v_sub_f32_e32 v98, v98, v247
	v_sub_f32_e32 v99, v99, v247
	v_xor_b32_e32 v220, 0x80000000, v247
	v_xor_b32_e32 v221, 0x80000000, v247
	v_xor_b32_e32 v222, 0x80000000, v247
	v_xor_b32_e32 v223, 0x80000000, v247
	v_xor_b32_e32 v224, 0x80000000, v247
	v_xor_b32_e32 v225, 0x80000000, v247
	v_xor_b32_e32 v226, 0x80000000, v247
	v_xor_b32_e32 v227, 0x80000000, v247
	v_xor_b32_e32 v228, 0x80000000, v247
	v_xor_b32_e32 v229, 0x80000000, v247
	v_xor_b32_e32 v230, 0x80000000, v247
	v_xor_b32_e32 v231, 0x80000000, v247
	v_xor_b32_e32 v232, 0x80000000, v247
	v_xor_b32_e32 v233, 0x80000000, v247
	v_xor_b32_e32 v234, 0x80000000, v247
	v_xor_b32_e32 v235, 0x80000000, v247
	s_add_i32 s6, s14, 2
	s_cmp_lt_u32 s6, s12
	s_cbranch_scc1 .LaA_w4_6
	s_waitcnt vmcnt(0)
	s_branch .LaA_wd_7

; #define LAS __attribute__((address_space(3)))
; __device__ __forceinline__ float fexp2(float x) { return __builtin_amdgcn_exp2f(x); }
; #define MFMA32(a, b, c) __builtin_amdgcn_mfma_f32_32x32x16_bf16((a), (b), (c), 0, 0, 0)
; __device__ __forceinline__ bf16x8 v_build(const VRaw& r, int ks) { return (bf16x8){r.lo[ks][0], r.lo[ks][1], r.lo[ks][2], r.lo[ks][3], r.hv[ks][0], r.hv[ks][1], r.hv[ks][2], r.hv[ks][3]}; }
; #define A_WAITBAR(ahead) do { if ((ahead) >= 2) asm volatile("s_waitcnt vmcnt(8)" ::: "memory"); else if ((ahead) == 1) asm volatile("s_waitcnt vmcnt(4)" ::: "memory"); else asm volatile("s_waitcnt vmcnt(0)" ::: "memory"); \
;         __builtin_amdgcn_s_barrier(); asm volatile("" ::: "memory"); } while (0)
; #define SB_ __builtin_amdgcn_sched_barrier(0)
; __device__ __forceinline__ void attnA_unit(const P2Ctx& C, int b, int h, int qb) {
;     ...
;       float ps = 0.f;
;       EX4_(s[0], 0); EX4_(s[0], 4); EX4_(s[0], 8); EX4_(s[0], 12); EX4_(s[1], 0); EX4_(s[1], 4); EX4_(s[1], 8); EX4_(s[1], 12);
;       SUM8_(s[0], 0); SUM8_(s[0], 8); SUM8_(s[1], 0); SUM8_(s[1], 8);
;       l = ps;
;       pf_[0] = pack_p(s[0], 0); pf_[1] = pack_p(s[0], 1); pf_[2] = pack_p(s[1], 0); pf_[3] = pack_p(s[1], 1); }
;       { const int lastt = NT - 1 < 2 ? NT - 1 : 2; A_WAITBAR(lastt - 1); } }
;     for (int kt = 1; kt < NT; ++kt) {
;         if (kt + 2 < NT && !(pf & 16)) A_DMA(kt + 2);
;         if (kt < ntw) {
;             A_QK(kt)
;             if (!(pf & 4)) {
;             const LAS unsigned char* vimg = lds + ((kt - 1) & 3) * 32768 + 16384;
;             VRaw va;
;             v_issue<4>(vimg, 0, lane, va);
;             A_MAX()
;             float fres = 1.0f; bool resc = false;
;             if (__any(mx > ATHR)) {
;                 const float dl = fmaxf(mx, 0.f);
;                 mhat += dl;
;                 fres = fexp2(-dl); resc = true;
; #pragma unroll
;                 for (int kb2 = 0; kb2 < 2; ++kb2)
; #pragma unroll
;                     for (int r = 0; r < 16; ++r) s[kb2][r] -= dl;
;             }
;             float ps = 0.f;
;             v_wait(va);
;             __builtin_amdgcn_s_setprio(1);
; #pragma unroll
;             for (int ks = 0; ks < 4; ++ks) o[0] = MFMA32(v_build(va, ks), pf_[ks], o[0]);
;             EX4_(s[0], 0); EX4_(s[0], 4); EX4_(s[0], 8); EX4_(s[0], 12);
;             SB_; v_issue<4>(vimg, 1, lane, va); v_wait(va);
.LaA_nodma_8:
	s_add_i32 s6, s14, 1
	s_and_b32 s6, s6, 3
	s_lshl_b32 s6, s6, 15
	v_add_u32_e32 v248, s6, v200
	v_add_u32_e32 v249, s6, v201
	v_add_u32_e32 v250, s6, v202
	v_add_u32_e32 v251, s6, v203
	ds_read_b128 v[100:103], v248
	ds_read_b128 v[104:107], v248 offset:4096
	ds_read_b128 v[108:111], v249
	ds_read_b128 v[112:115], v249 offset:4096
	ds_read_b128 v[116:119], v250
	ds_read_b128 v[120:123], v250 offset:4096
	ds_read_b128 v[124:127], v251
	ds_read_b128 v[128:131], v251 offset:4096
	v_exp_f32_e32 v68, v68
	v_exp_f32_e32 v69, v69
	v_exp_f32_e32 v70, v70
	v_exp_f32_e32 v71, v71
	v_exp_f32_e32 v72, v72
	v_exp_f32_e32 v73, v73
	v_exp_f32_e32 v74, v74
	v_exp_f32_e32 v75, v75
	v_exp_f32_e32 v76, v76
	v_exp_f32_e32 v77, v77
	v_exp_f32_e32 v78, v78
	v_exp_f32_e32 v79, v79
	v_exp_f32_e32 v80, v80
	v_exp_f32_e32 v81, v81
	v_exp_f32_e32 v82, v82
	v_exp_f32_e32 v83, v83
	v_exp_f32_e32 v84, v84
	v_exp_f32_e32 v85, v85
	v_exp_f32_e32 v86, v86
	v_exp_f32_e32 v87, v87
	v_exp_f32_e32 v88, v88
	v_exp_f32_e32 v89, v89
	v_exp_f32_e32 v90, v90
	v_exp_f32_e32 v91, v91
	v_exp_f32_e32 v92, v92
	v_exp_f32_e32 v93, v93
	v_exp_f32_e32 v94, v94
	v_exp_f32_e32 v95, v95
	v_exp_f32_e32 v96, v96
	v_exp_f32_e32 v97, v97
	v_exp_f32_e32 v98, v98
	v_exp_f32_e32 v99, v99
	v_add_f32_e32 v245, v68, v69
	v_add_f32_e32 v243, v70, v71
	v_add_f32_e32 v245, v245, v243
	v_add_f32_e32 v243, v72, v73
	v_add_f32_e32 v242, v74, v75
	v_add_f32_e32 v243, v243, v242
	v_add_f32_e32 v245, v245, v243
	v_add_f32_e32 v246, v76, v77
	v_add_f32_e32 v243, v78, v79
	v_add_f32_e32 v246, v246, v243
	v_add_f32_e32 v243, v80, v81
	v_add_f32_e32 v242, v82, v83
	v_add_f32_e32 v243, v243, v242
	v_add_f32_e32 v246, v246, v243
	v_add_f32_e32 v245, v245, v246
	v_add_f32_e32 v246, v84, v85
	v_add_f32_e32 v243, v86, v87
	v_add_f32_e32 v246, v246, v243
	v_add_f32_e32 v243, v88, v89
	v_add_f32_e32 v242, v90, v91
	v_add_f32_e32 v243, v243, v242
	v_add_f32_e32 v246, v246, v243
	v_add_f32_e32 v245, v245, v246
	v_add_f32_e32 v246, v92, v93
	v_add_f32_e32 v243, v94, v95
	v_add_f32_e32 v246, v246, v243
	v_add_f32_e32 v243, v96, v97
	v_add_f32_e32 v242, v98, v99
	v_add_f32_e32 v243, v243, v242
	v_add_f32_e32 v246, v246, v243
	v_add_f32_e32 v245, v245, v246
	v_mov_b32_e32 v241, v245
	v_cvt_pk_bf16_f32 v180, v68, v69
	v_cvt_pk_bf16_f32 v181, v70, v71
	v_cvt_pk_bf16_f32 v182, v72, v73
	v_cvt_pk_bf16_f32 v183, v74, v75
	v_cvt_pk_bf16_f32 v184, v76, v77
	v_cvt_pk_bf16_f32 v185, v78, v79
	v_cvt_pk_bf16_f32 v186, v80, v81
	v_cvt_pk_bf16_f32 v187, v82, v83
	v_cvt_pk_bf16_f32 v188, v84, v85
	v_cvt_pk_bf16_f32 v189, v86, v87
	v_cvt_pk_bf16_f32 v190, v88, v89
	v_cvt_pk_bf16_f32 v191, v90, v91
	v_cvt_pk_bf16_f32 v192, v92, v93
	v_cvt_pk_bf16_f32 v193, v94, v95
	v_cvt_pk_bf16_f32 v194, v96, v97
	v_cvt_pk_bf16_f32 v195, v98, v99
	s_mov_b32 s14, 1
.LaA_loop:
	s_cmp_lt_u32 s14, s13
	s_cbranch_scc0 .LaA_pvonly
	s_add_i32 s7, s14, -1
	s_and_b32 s7, s7, 3
	s_lshl_b32 s7, s7, 15
	v_add_u32_e32 v237, s7, v204
	s_waitcnt lgkmcnt(0)
	v_mfma_f32_32x32x16_bf16 v[68:83], v[100:103], v[164:167], v[220:235]
	ds_read_b64_tr_b16 v[132:133], v237 offset:0
	ds_read_b64_tr_b16 v[134:135], v237 offset:2048
	v_mfma_f32_32x32x16_bf16 v[84:99], v[104:107], v[164:167], v[220:235]
	ds_read_b64_tr_b16 v[136:137], v237 offset:4096
	ds_read_b64_tr_b16 v[138:139], v237 offset:6144
	v_mfma_f32_32x32x16_bf16 v[68:83], v[108:111], v[168:171], v[68:83]
	ds_read_b64_tr_b16 v[140:141], v237 offset:8192
	ds_read_b64_tr_b16 v[142:143], v237 offset:10240
	v_mfma_f32_32x32x16_bf16 v[84:99], v[112:115], v[168:171], v[84:99]
	ds_read_b64_tr_b16 v[144:145], v237 offset:12288
	ds_read_b64_tr_b16 v[146:147], v237 offset:14336
	v_mfma_f32_32x32x16_bf16 v[68:83], v[116:119], v[172:175], v[68:83]
	v_mfma_f32_32x32x16_bf16 v[84:99], v[120:123], v[172:175], v[84:99]
	v_mfma_f32_32x32x16_bf16 v[68:83], v[124:127], v[176:179], v[68:83]
	v_mfma_f32_32x32x16_bf16 v[84:99], v[128:131], v[176:179], v[84:99]
	s_waitcnt lgkmcnt(0)
	ds_read_b64_tr_b16 v[148:149], v237 offset:512
	ds_read_b64_tr_b16 v[150:151], v237 offset:2560
	v_mfma_f32_32x32x16_bf16 v[4:19], v[132:135], v[180:183], v[4:19]
	ds_read_b64_tr_b16 v[152:153], v237 offset:4608
	ds_read_b64_tr_b16 v[154:155], v237 offset:6656
	ds_read_b64_tr_b16 v[156:157], v237 offset:8704
	v_mfma_f32_32x32x16_bf16 v[4:19], v[136:139], v[184:187], v[4:19]
	ds_read_b64_tr_b16 v[158:159], v237 offset:10752
	ds_read_b64_tr_b16 v[160:161], v237 offset:12800
	ds_read_b64_tr_b16 v[162:163], v237 offset:14848
	v_mfma_f32_32x32x16_bf16 v[4:19], v[140:143], v[188:191], v[4:19]
	v_mfma_f32_32x32x16_bf16 v[4:19], v[144:147], v[192:195], v[4:19]
	s_lshl_b32 s6, s14, 6
	s_cmp_gt_i32 s6, s26
	s_cbranch_scc1 .LaA_near_10
.LaA_far_11:
	s_waitcnt lgkmcnt(0)
	ds_read_b64_tr_b16 v[132:133], v237 offset:1024
	ds_read_b64_tr_b16 v[134:135], v237 offset:3072
	v_mfma_f32_32x32x16_bf16 v[20:35], v[148:151], v[180:183], v[20:35]
	ds_read_b64_tr_b16 v[136:137], v237 offset:5120
	ds_read_b64_tr_b16 v[138:139], v237 offset:7168
	ds_read_b64_tr_b16 v[140:141], v237 offset:9216
	v_max_f32_e32 v242, v68, v69
	v_max_f32_e32 v243, v84, v85
	v_max3_f32 v242, v242, v70, v71
	v_max3_f32 v243, v243, v86, v87
	v_max3_f32 v242, v242, v72, v73
	v_mfma_f32_32x32x16_bf16 v[20:35], v[152:155], v[184:187], v[20:35]
	ds_read_b64_tr_b16 v[142:143], v237 offset:11264
	ds_read_b64_tr_b16 v[144:145], v237 offset:13312
	ds_read_b64_tr_b16 v[146:147], v237 offset:15360
	v_max3_f32 v243, v243, v88, v89
	v_max3_f32 v242, v242, v74, v75
	v_max3_f32 v243, v243, v90, v91
	v_max3_f32 v242, v242, v76, v77
	v_max3_f32 v243, v243, v92, v93
	v_mfma_f32_32x32x16_bf16 v[20:35], v[156:159], v[188:191], v[20:35]
	v_max3_f32 v242, v242, v78, v79
	v_max3_f32 v243, v243, v94, v95
	v_max3_f32 v242, v242, v80, v81
	v_max3_f32 v243, v243, v96, v97
	v_max3_f32 v242, v242, v82, v83
	v_mfma_f32_32x32x16_bf16 v[20:35], v[160:163], v[192:195], v[20:35]
	v_max3_f32 v243, v243, v98, v99
	v_max_f32_e32 v242, v242, v243
	v_mov_b32_e32 v243, v242
	s_nop 1
	v_permlane32_swap_b32 v243, v242
	v_max_f32_e32 v247, v243, v242
	v_cmp_lt_f32_e32 vcc, 0x41000000, v247
	s_cmp_lg_u64 vcc, 0
	s_cbranch_scc1 .LaA_resc_pre
.LaA_resc_back:
	s_add_i32 s6, s14, 2
	s_cmp_lt_u32 s6, s12
	s_cbranch_scc1 .LaA_w4_12
	s_waitcnt vmcnt(0)
	s_branch .LaA_wd_13

; #define MFMA32(a, b, c) __builtin_amdgcn_mfma_f32_32x32x16_bf16((a), (b), (c), 0, 0, 0)
; __device__ __forceinline__ bf16x8 v_build(const VRaw& r, int ks) { return (bf16x8){r.lo[ks][0], r.lo[ks][1], r.lo[ks][2], r.lo[ks][3], r.hv[ks][0], r.hv[ks][1], r.hv[ks][2], r.hv[ks][3]}; }
; #define SB_ __builtin_amdgcn_sched_barrier(0)
; #define EX4_(S, B) do { S[B] = fexp2(S[B]); S[B + 1] = fexp2(S[B + 1]); S[B + 2] = fexp2(S[B + 2]); S[B + 3] = fexp2(S[B + 3]); } while (0)
; #define SUM8_(S, B) do { ps += ((S[B] + S[B + 1]) + (S[B + 2] + S[B + 3])) + ((S[B + 4] + S[B + 5]) + (S[B + 6] + S[B + 7])); } while (0)
; __device__ __forceinline__ void attnA_unit(const P2Ctx& C, int b, int h, int qb) {
;     ...
;             EX4_(s[0], 0); EX4_(s[0], 4); EX4_(s[0], 8); EX4_(s[0], 12);
;             SB_; v_issue<4>(vimg, 1, lane, va); v_wait(va);
; #pragma unroll
;             for (int ks = 0; ks < 4; ++ks) o[1] = MFMA32(v_build(va, ks), pf_[ks], o[1]);
;             EX4_(s[1], 0); EX4_(s[1], 4); EX4_(s[1], 8); EX4_(s[1], 12);
;             SB_; v_issue<4>(vimg, 2, lane, va); v_wait(va);
; #pragma unroll
;             for (int ks = 0; ks < 4; ++ks) o[2] = MFMA32(v_build(va, ks), pf_[ks], o[2]);
;             SUM8_(s[0], 0); SUM8_(s[0], 8); SUM8_(s[1], 0); SUM8_(s[1], 8);
;             SB_; v_issue<4>(vimg, 3, lane, va); v_wait(va);
;             o[3] = MFMA32(v_build(va, 0), pf_[0], o[3]); pf_[0] = pack_p(s[0], 0);
;             o[3] = MFMA32(v_build(va, 1), pf_[1], o[3]); pf_[1] = pack_p(s[0], 1);
;             o[3] = MFMA32(v_build(va, 2), pf_[2], o[3]); pf_[2] = pack_p(s[1], 0);
;             o[3] = MFMA32(v_build(va, 3), pf_[3], o[3]); pf_[3] = pack_p(s[1], 1);
.LaA_nodma_14:
	s_waitcnt lgkmcnt(0)
	ds_read_b64_tr_b16 v[148:149], v237 offset:1536
	ds_read_b64_tr_b16 v[150:151], v237 offset:3584
	v_mfma_f32_32x32x16_bf16 v[36:51], v[132:135], v[180:183], v[36:51]
	ds_read_b64_tr_b16 v[152:153], v237 offset:5632
	ds_read_b64_tr_b16 v[154:155], v237 offset:7680
	ds_read_b64_tr_b16 v[156:157], v237 offset:9728
	v_exp_f32_e32 v68, v68
	v_exp_f32_e32 v69, v69
	v_exp_f32_e32 v70, v70
	v_exp_f32_e32 v71, v71
	v_mfma_f32_32x32x16_bf16 v[36:51], v[136:139], v[184:187], v[36:51]
	ds_read_b64_tr_b16 v[158:159], v237 offset:11776
	ds_read_b64_tr_b16 v[160:161], v237 offset:13824
	ds_read_b64_tr_b16 v[162:163], v237 offset:15872
	v_exp_f32_e32 v72, v72
	v_exp_f32_e32 v73, v73
	v_exp_f32_e32 v74, v74
	v_exp_f32_e32 v75, v75
	v_mfma_f32_32x32x16_bf16 v[36:51], v[140:143], v[188:191], v[36:51]
	v_exp_f32_e32 v76, v76
	v_exp_f32_e32 v77, v77
	v_exp_f32_e32 v78, v78
	v_exp_f32_e32 v79, v79
	v_mfma_f32_32x32x16_bf16 v[36:51], v[144:147], v[192:195], v[36:51]
	v_exp_f32_e32 v80, v80
	v_exp_f32_e32 v81, v81
	v_exp_f32_e32 v82, v82
	v_exp_f32_e32 v83, v83
	s_waitcnt lgkmcnt(0)
	s_add_i32 s6, s14, 1
	s_and_b32 s6, s6, 3
	s_lshl_b32 s6, s6, 15
	v_add_u32_e32 v248, s6, v200
	v_add_u32_e32 v249, s6, v201
	v_add_u32_e32 v250, s6, v202
	v_add_u32_e32 v251, s6, v203
	ds_read_b128 v[100:103], v248
	ds_read_b128 v[104:107], v248 offset:4096
	ds_read_b128 v[108:111], v249
	ds_read_b128 v[112:115], v249 offset:4096
	ds_read_b128 v[116:119], v250
	ds_read_b128 v[120:123], v250 offset:4096
	ds_read_b128 v[124:127], v251
	ds_read_b128 v[128:131], v251 offset:4096
	v_mfma_f32_32x32x16_bf16 v[52:67], v[148:151], v[180:183], v[52:67]
	v_exp_f32_e32 v84, v84
	v_exp_f32_e32 v85, v85
	v_exp_f32_e32 v86, v86
	v_exp_f32_e32 v87, v87
	v_exp_f32_e32 v88, v88
	v_exp_f32_e32 v89, v89
	v_exp_f32_e32 v90, v90
	v_exp_f32_e32 v91, v91
	v_cvt_pk_bf16_f32 v180, v68, v69
	v_cvt_pk_bf16_f32 v181, v70, v71
	v_cvt_pk_bf16_f32 v182, v72, v73
	v_cvt_pk_bf16_f32 v183, v74, v75
	v_mfma_f32_32x32x16_bf16 v[52:67], v[152:155], v[184:187], v[52:67]
	v_exp_f32_e32 v92, v92
	v_exp_f32_e32 v93, v93
	v_exp_f32_e32 v94, v94
	v_exp_f32_e32 v95, v95
	v_exp_f32_e32 v96, v96
	v_exp_f32_e32 v97, v97
	v_exp_f32_e32 v98, v98
	v_exp_f32_e32 v99, v99
	v_cvt_pk_bf16_f32 v184, v76, v77
	v_cvt_pk_bf16_f32 v185, v78, v79
	v_cvt_pk_bf16_f32 v186, v80, v81
	v_cvt_pk_bf16_f32 v187, v82, v83
	v_mfma_f32_32x32x16_bf16 v[52:67], v[156:159], v[188:191], v[52:67]
	v_add_f32_e32 v245, v68, v69
	v_add_f32_e32 v243, v70, v71
	v_add_f32_e32 v245, v245, v243
	v_add_f32_e32 v243, v72, v73
	v_add_f32_e32 v242, v74, v75
	v_add_f32_e32 v243, v243, v242
	v_add_f32_e32 v245, v245, v243
	v_add_f32_e32 v246, v76, v77
	v_add_f32_e32 v243, v78, v79
	v_add_f32_e32 v246, v246, v243
	v_add_f32_e32 v243, v80, v81
	v_add_f32_e32 v242, v82, v83
	v_add_f32_e32 v243, v243, v242
	v_add_f32_e32 v246, v246, v243
	v_add_f32_e32 v245, v245, v246
	v_cvt_pk_bf16_f32 v188, v84, v85
	v_cvt_pk_bf16_f32 v189, v86, v87
	v_cvt_pk_bf16_f32 v190, v88, v89
	v_cvt_pk_bf16_f32 v191, v90, v91
	v_mfma_f32_32x32x16_bf16 v[52:67], v[160:163], v[192:195], v[52:67]
	v_add_f32_e32 v246, v84, v85
	v_add_f32_e32 v243, v86, v87
	v_add_f32_e32 v246, v246, v243
	v_add_f32_e32 v243, v88, v89
	v_add_f32_e32 v242, v90, v91
	v_add_f32_e32 v243, v243, v242
	v_add_f32_e32 v246, v246, v243
	v_add_f32_e32 v245, v245, v246
	v_add_f32_e32 v246, v92, v93
	v_add_f32_e32 v243, v94, v95
	v_add_f32_e32 v246, v246, v243
	v_add_f32_e32 v243, v96, v97
	v_add_f32_e32 v242, v98, v99
	v_add_f32_e32 v243, v243, v242
	v_add_f32_e32 v246, v246, v243
	v_add_f32_e32 v245, v245, v246
	v_cvt_pk_bf16_f32 v192, v92, v93
	v_cvt_pk_bf16_f32 v193, v94, v95
	v_cvt_pk_bf16_f32 v194, v96, v97
	v_cvt_pk_bf16_f32 v195, v98, v99
	s_cmp_lg_u32 s25, 0
	s_cbranch_scc1 .LaA_resc_post

; #define A_WAITBAR(ahead) do { if ((ahead) >= 2) asm volatile("s_waitcnt vmcnt(8)" ::: "memory"); else if ((ahead) == 1) asm volatile("s_waitcnt vmcnt(4)" ::: "memory"); else asm volatile("s_waitcnt vmcnt(0)" ::: "memory"); \
;         __builtin_amdgcn_s_barrier(); asm volatile("" ::: "memory"); } while (0)
; __device__ __forceinline__ void attnA_unit(const P2Ctx& C, int b, int h, int qb) {
;     ...
;             if (resc) {
;                 l *= fres;
; #pragma unroll
;                 for (int cb = 0; cb < 4; ++cb)
; #pragma unroll
;                     for (int r = 0; r < 16; ++r) o[cb][r] *= fres;
;             }
;             l += ps;
;             }
;         } else if (kt - 1 < ntw && !(pf & 2)) { A_PV(kt - 1); }
;         { const int lastt = NT - 1 < kt + 2 ? NT - 1 : kt + 2; const int ahead = lastt - (kt + 1); A_WAITBAR(ahead); }
.LaA_resc_post:
	s_nop 7
	s_nop 3
	v_mul_f32_e32 v4, v244, v4
	v_mul_f32_e32 v5, v244, v5
	v_mul_f32_e32 v6, v244, v6
	v_mul_f32_e32 v7, v244, v7
	v_mul_f32_e32 v8, v244, v8
	v_mul_f32_e32 v9, v244, v9
	v_mul_f32_e32 v10, v244, v10
	v_mul_f32_e32 v11, v244, v11
	v_mul_f32_e32 v12, v244, v12
	v_mul_f32_e32 v13, v244, v13
	v_mul_f32_e32 v14, v244, v14
	v_mul_f32_e32 v15, v244, v15
	v_mul_f32_e32 v16, v244, v16
	v_mul_f32_e32 v17, v244, v17
	v_mul_f32_e32 v18, v244, v18
	v_mul_f32_e32 v19, v244, v19
	v_mul_f32_e32 v20, v244, v20
	v_mul_f32_e32 v21, v244, v21
	v_mul_f32_e32 v22, v244, v22
	v_mul_f32_e32 v23, v244, v23
	v_mul_f32_e32 v24, v244, v24
	v_mul_f32_e32 v25, v244, v25
	v_mul_f32_e32 v26, v244, v26
	v_mul_f32_e32 v27, v244, v27
	v_mul_f32_e32 v28, v244, v28
	v_mul_f32_e32 v29, v244, v29
	v_mul_f32_e32 v30, v244, v30
	v_mul_f32_e32 v31, v244, v31
	v_mul_f32_e32 v32, v244, v32
	v_mul_f32_e32 v33, v244, v33
	v_mul_f32_e32 v34, v244, v34
	v_mul_f32_e32 v35, v244, v35
	v_mul_f32_e32 v36, v244, v36
	v_mul_f32_e32 v37, v244, v37
	v_mul_f32_e32 v38, v244, v38
	v_mul_f32_e32 v39, v244, v39
	v_mul_f32_e32 v40, v244, v40
	v_mul_f32_e32 v41, v244, v41
	v_mul_f32_e32 v42, v244, v42
	v_mul_f32_e32 v43, v244, v43
	v_mul_f32_e32 v44, v244, v44
	v_mul_f32_e32 v45, v244, v45
	v_mul_f32_e32 v46, v244, v46
	v_mul_f32_e32 v47, v244, v47
	v_mul_f32_e32 v48, v244, v48
	v_mul_f32_e32 v49, v244, v49
	v_mul_f32_e32 v50, v244, v50
	v_mul_f32_e32 v51, v244, v51
	v_mul_f32_e32 v52, v244, v52
	v_mul_f32_e32 v53, v244, v53
	v_mul_f32_e32 v54, v244, v54
	v_mul_f32_e32 v55, v244, v55
	v_mul_f32_e32 v56, v244, v56
	v_mul_f32_e32 v57, v244, v57
	v_mul_f32_e32 v58, v244, v58
	v_mul_f32_e32 v59, v244, v59
	v_mul_f32_e32 v60, v244, v60
	v_mul_f32_e32 v61, v244, v61
	v_mul_f32_e32 v62, v244, v62
	v_mul_f32_e32 v63, v244, v63
	v_mul_f32_e32 v64, v244, v64
	v_mul_f32_e32 v65, v244, v65
	v_mul_f32_e32 v66, v244, v66
	v_mul_f32_e32 v67, v244, v67
	v_mul_f32_e32 v241, v244, v241
	s_mov_b32 s25, 0
	s_branch .LaA_resc_done
.LaA_pvonly:
	s_add_i32 s6, s14, 2
	s_cmp_lt_u32 s6, s12
	s_cbranch_scc1 .LaA_w4_17
	s_waitcnt vmcnt(0)
	s_branch .LaA_wd_18

; #define LAS __attribute__((address_space(3)))
; __device__ __forceinline__ void attnA_unit(const P2Ctx& C, int b, int h, int qb) {
;     ...
;     if (NT - 1 < ntw && !(pf & 2)) A_PV(NT - 1);
;     __syncthreads();
;     ...
;     l += __shfl_xor(l, 32);
;     const float inv = 1.0f / l;
;     LAS float* X2 = (LAS float*)(lds + 65536);
;     if (comp == 1) {
; #pragma unroll
;         for (int cb = 0; cb < 4; ++cb)
; #pragma unroll
;             for (int r = 0; r < 16; ++r) X2[((qs * 4 + cb) * 16 + r) * 64 + lane] = o[cb][r] * inv;
;     }
.LaA_nofinalpv_21:
	s_waitcnt lgkmcnt(0)
	s_barrier
	v_mov_b32_e32 v243, v241
	s_nop 1
	v_permlane32_swap_b32 v243, v241
	v_add_f32_e32 v241, v243, v241
	v_rcp_f32_e32 v241, v241
	s_lshl_b32 s6, s9, 14
	s_add_i32 s6, s6, 0x10000
	v_lshlrev_b32_e32 v2, 2, v219
	v_add_u32_e32 v2, s6, v2
	s_cmp_eq_u32 s8, 0
	s_cbranch_scc1 .LaA_comp0_22
	s_nop 7
	s_nop 3
	v_mul_f32_e32 v68, v4, v241
	ds_write_b32 v2, v68 offset:0
	v_mul_f32_e32 v69, v5, v241
	ds_write_b32 v2, v69 offset:256
	v_mul_f32_e32 v68, v6, v241
	ds_write_b32 v2, v68 offset:512
	v_mul_f32_e32 v69, v7, v241
	ds_write_b32 v2, v69 offset:768
	v_mul_f32_e32 v68, v8, v241
	ds_write_b32 v2, v68 offset:1024
	v_mul_f32_e32 v69, v9, v241
	ds_write_b32 v2, v69 offset:1280
	v_mul_f32_e32 v68, v10, v241
	ds_write_b32 v2, v68 offset:1536
	v_mul_f32_e32 v69, v11, v241
	ds_write_b32 v2, v69 offset:1792
	v_mul_f32_e32 v68, v12, v241
	ds_write_b32 v2, v68 offset:2048
	v_mul_f32_e32 v69, v13, v241
	ds_write_b32 v2, v69 offset:2304
	v_mul_f32_e32 v68, v14, v241
	ds_write_b32 v2, v68 offset:2560
	v_mul_f32_e32 v69, v15, v241
	ds_write_b32 v2, v69 offset:2816
	v_mul_f32_e32 v68, v16, v241
	ds_write_b32 v2, v68 offset:3072
	v_mul_f32_e32 v69, v17, v241
	ds_write_b32 v2, v69 offset:3328
	v_mul_f32_e32 v68, v18, v241
	ds_write_b32 v2, v68 offset:3584
	v_mul_f32_e32 v69, v19, v241
	ds_write_b32 v2, v69 offset:3840
	v_mul_f32_e32 v68, v20, v241
	ds_write_b32 v2, v68 offset:4096
	v_mul_f32_e32 v69, v21, v241
	ds_write_b32 v2, v69 offset:4352
	v_mul_f32_e32 v68, v22, v241
	ds_write_b32 v2, v68 offset:4608
	v_mul_f32_e32 v69, v23, v241
	ds_write_b32 v2, v69 offset:4864
	v_mul_f32_e32 v68, v24, v241
	ds_write_b32 v2, v68 offset:5120
	v_mul_f32_e32 v69, v25, v241
	ds_write_b32 v2, v69 offset:5376
	v_mul_f32_e32 v68, v26, v241
	ds_write_b32 v2, v68 offset:5632
	v_mul_f32_e32 v69, v27, v241
	ds_write_b32 v2, v69 offset:5888
	v_mul_f32_e32 v68, v28, v241
	ds_write_b32 v2, v68 offset:6144
	v_mul_f32_e32 v69, v29, v241
	ds_write_b32 v2, v69 offset:6400
	v_mul_f32_e32 v68, v30, v241
	ds_write_b32 v2, v68 offset:6656
	v_mul_f32_e32 v69, v31, v241
	ds_write_b32 v2, v69 offset:6912
	v_mul_f32_e32 v68, v32, v241
	ds_write_b32 v2, v68 offset:7168
	v_mul_f32_e32 v69, v33, v241
	ds_write_b32 v2, v69 offset:7424
	v_mul_f32_e32 v68, v34, v241
	ds_write_b32 v2, v68 offset:7680
	v_mul_f32_e32 v69, v35, v241
	ds_write_b32 v2, v69 offset:7936
	v_mul_f32_e32 v68, v36, v241
	ds_write_b32 v2, v68 offset:8192
	v_mul_f32_e32 v69, v37, v241
	ds_write_b32 v2, v69 offset:8448
	v_mul_f32_e32 v68, v38, v241
	ds_write_b32 v2, v68 offset:8704
	v_mul_f32_e32 v69, v39, v241
	ds_write_b32 v2, v69 offset:8960
	v_mul_f32_e32 v68, v40, v241
	ds_write_b32 v2, v68 offset:9216
	v_mul_f32_e32 v69, v41, v241
	ds_write_b32 v2, v69 offset:9472
	v_mul_f32_e32 v68, v42, v241
	ds_write_b32 v2, v68 offset:9728
	v_mul_f32_e32 v69, v43, v241
	ds_write_b32 v2, v69 offset:9984
	v_mul_f32_e32 v68, v44, v241
	ds_write_b32 v2, v68 offset:10240
	v_mul_f32_e32 v69, v45, v241
	ds_write_b32 v2, v69 offset:10496
	v_mul_f32_e32 v68, v46, v241
	ds_write_b32 v2, v68 offset:10752
	v_mul_f32_e32 v69, v47, v241
	ds_write_b32 v2, v69 offset:11008
	v_mul_f32_e32 v68, v48, v241
	ds_write_b32 v2, v68 offset:11264
	v_mul_f32_e32 v69, v49, v241
	ds_write_b32 v2, v69 offset:11520
	v_mul_f32_e32 v68, v50, v241
	ds_write_b32 v2, v68 offset:11776
	v_mul_f32_e32 v69, v51, v241
	ds_write_b32 v2, v69 offset:12032
	v_mul_f32_e32 v68, v52, v241
	ds_write_b32 v2, v68 offset:12288
	v_mul_f32_e32 v69, v53, v241
	ds_write_b32 v2, v69 offset:12544
	v_mul_f32_e32 v68, v54, v241
	ds_write_b32 v2, v68 offset:12800
	v_mul_f32_e32 v69, v55, v241
	ds_write_b32 v2, v69 offset:13056
	v_mul_f32_e32 v68, v56, v241
	ds_write_b32 v2, v68 offset:13312
	v_mul_f32_e32 v69, v57, v241
	ds_write_b32 v2, v69 offset:13568
	v_mul_f32_e32 v68, v58, v241
	ds_write_b32 v2, v68 offset:13824
	v_mul_f32_e32 v69, v59, v241
	ds_write_b32 v2, v69 offset:14080
	v_mul_f32_e32 v68, v60, v241
	ds_write_b32 v2, v68 offset:14336
	v_mul_f32_e32 v69, v61, v241
	ds_write_b32 v2, v69 offset:14592
	v_mul_f32_e32 v68, v62, v241
	ds_write_b32 v2, v68 offset:14848
	v_mul_f32_e32 v69, v63, v241
	ds_write_b32 v2, v69 offset:15104
	v_mul_f32_e32 v68, v64, v241
	ds_write_b32 v2, v68 offset:15360
	v_mul_f32_e32 v69, v65, v241
	ds_write_b32 v2, v69 offset:15616
	v_mul_f32_e32 v68, v66, v241
	ds_write_b32 v2, v68 offset:15872
	v_mul_f32_e32 v69, v67, v241
	ds_write_b32 v2, v69 offset:16128
	s_waitcnt lgkmcnt(0)
	s_barrier
	s_branch .LaA_epiend_23
; __device__ __forceinline__ void attnA_unit(const P2Ctx& C, int b, int h, int qb) {
;     ...
;     if (comp == 1) {
; #pragma unroll
;         for (int cb = 0; cb < 4; ++cb)
; #pragma unroll
;             for (int r = 0; r < 16; ++r) X2[((qs * 4 + cb) * 16 + r) * 64 + lane] = o[cb][r] * inv;
;     }
;     __syncthreads();
;     if (comp == 0) {
	s_nop 0
	s_nop 0
	s_nop 0
	s_nop 0
	s_nop 0
	s_nop 0
	s_nop 0
	s_nop 0
	s_nop 0
	s_nop 0
	s_nop 0
	s_nop 0
	s_nop 0
	s_nop 0
	s_nop 0
	s_nop 0
	s_nop 0
	s_nop 0
	s_nop 0
	s_nop 0
	s_nop 0
	s_nop 0
	s_nop 0
	s_nop 0
	s_nop 0
	s_nop 0
	s_nop 0
	s_nop 0
	s_nop 0
	s_nop 0
	s_nop 0
	s_nop 0
	s_nop 0
	s_nop 0
	s_nop 0
	s_nop 0
	s_nop 0
	s_nop 0
	s_nop 0
	s_nop 0
	s_nop 0
	s_nop 0
	s_nop 0
	s_nop 0
	s_nop 0
	s_nop 0
	s_nop 0
	s_nop 0
	s_nop 0
	s_nop 0
	s_nop 0
	s_nop 0
	s_nop 0
	s_nop 0
	s_nop 0
	s_nop 0
	s_nop 0
	s_nop 0
	s_nop 0
	s_nop 0
	s_nop 0
	s_nop 0
	s_nop 0
	s_nop 0
	s_nop 0
	s_nop 0
	s_nop 0
	s_nop 0
	s_nop 0
	s_nop 0
	s_nop 0
	s_nop 0
	s_nop 0
	s_nop 0
	s_nop 0
	s_nop 0
	s_nop 0
	s_nop 0
	s_nop 0
	s_nop 0
	s_nop 0
	s_nop 0
	s_nop 0
	s_nop 0
	s_nop 0
	s_nop 0
	s_nop 0
	s_nop 0
	s_nop 0
	s_nop 0
	s_nop 0
	s_nop 0
	s_nop 0
	s_nop 0
	s_nop 0
	s_nop 0
	s_nop 0
	s_nop 0
	s_nop 0
	s_nop 0
	s_nop 0
	s_nop 0
	s_nop 0
	s_nop 0
	s_nop 0
	s_nop 0
	s_nop 0
	s_nop 0
	s_nop 0
	s_nop 0
	s_nop 0
	s_nop 0
	s_nop 0
	s_nop 0
	s_nop 0
	s_nop 0
	s_nop 0
	s_nop 0
	s_nop 0
	s_nop 0
	s_nop 0
	s_nop 0
	s_nop 0
	s_nop 0
	s_nop 0
	s_nop 0
	s_nop 0
	s_nop 0
	s_nop 0
	s_nop 0
	s_nop 0
	s_nop 0
	s_nop 0
	s_nop 0
	s_nop 0
	s_nop 0
	s_nop 0
	s_nop 0
	s_nop 0
	s_nop 0
	s_nop 0
	s_nop 0
	s_nop 0
	s_nop 0
	s_nop 0
	s_nop 0
	s_nop 0
	s_nop 0
	s_nop 0
	s_nop 0
	s_nop 0
	s_nop 0
	s_nop 0
	s_nop 0
	s_nop 0
	s_nop 0
	s_nop 0
	s_nop 0
	s_nop 0
	s_nop 0
	s_nop 0
	s_nop 0
	s_nop 0
	s_nop 0
	s_nop 0
	s_nop 0
	s_nop 0
	s_nop 0
	s_nop 0
	s_nop 0
	s_nop 0
	s_nop 0
	s_nop 0
	s_nop 0
	s_nop 0
	s_nop 0
	s_nop 0
	s_nop 0
	s_nop 0
	s_nop 0
	s_nop 0
	s_nop 0
	s_nop 0
	s_nop 0
	s_nop 0
	s_nop 0
	s_nop 0
	s_nop 0
	s_nop 0
	s_nop 0
	s_nop 0
	s_nop 0
	s_nop 0
	s_nop 0
	s_nop 0
	s_nop 0
	s_nop 0
	s_nop 0
	s_nop 0
	s_nop 0
	s_nop 0
	s_nop 0
	s_nop 0
	s_nop 0
	s_nop 0
	s_nop 0
	s_nop 0
	s_nop 0
	s_nop 0
	s_nop 0
	s_nop 0
	s_nop 0
	s_nop 0
	s_nop 0
	s_nop 0
	s_nop 0
	s_nop 0
	s_nop 0
	s_nop 0
	s_nop 0
	s_nop 0
	s_nop 0
	s_nop 0
	s_nop 0
	s_nop 0
	s_nop 0
	s_nop 0
	s_nop 0
	s_nop 0
	s_nop 0
	s_nop 0
	s_nop 0
	s_nop 0
	s_nop 0
	s_nop 0
	s_nop 0
	s_nop 0
	s_nop 0
	s_nop 0
	s_nop 0
	s_nop 0
	s_nop 0
	s_nop 0
	s_nop 0
	s_nop 0
	s_nop 0
	s_nop 0
	s_nop 0
	s_nop 0
	s_nop 0
	s_nop 0
	s_nop 0
	s_nop 0
	s_nop 0
	s_nop 0
	s_nop 0
	s_nop 0
	s_nop 0
	s_nop 0
	s_nop 0
	s_nop 0
	s_nop 0
	s_nop 0
	s_nop 0
	s_nop 0
	s_nop 0
	s_nop 0
	s_nop 0
	s_nop 0
	s_nop 0
	s_nop 0
	s_nop 0
	s_nop 0
	s_nop 0
	s_nop 0
	s_nop 0
	s_nop 0
	s_nop 0
	s_nop 0
	s_nop 0
	s_nop 0
	s_nop 0
	s_nop 0
	s_nop 0
	s_nop 0
	s_nop 0
	s_nop 0
	s_nop 0
	s_nop 0
	s_nop 0
	s_nop 0
	s_nop 0
	s_nop 0
	s_nop 0
	s_nop 0
	s_nop 0
	s_nop 0
	s_nop 0
	s_nop 0
	s_nop 0
	s_nop 0
	s_nop 0
	s_nop 0
	s_nop 0
	s_nop 0
	s_nop 0
	s_nop 0
	s_nop 0
	s_nop 0
	s_nop 0
	s_nop 0
	s_nop 0
	s_nop 0
	s_nop 0
	s_nop 0
	s_nop 0
	s_nop 0
	s_nop 0
	s_nop 0
	s_nop 0
	s_nop 0
	s_nop 0
	s_nop 0
	s_nop 0
	s_nop 0
	s_nop 0
	s_nop 0
	s_nop 0
	s_nop 0
	s_nop 0
	s_nop 0
	s_nop 0
	s_nop 0
	s_nop 0
	s_nop 0
	s_nop 0
	s_nop 0
	s_nop 0
	s_nop 0
	s_nop 0
	s_nop 0
	s_nop 0
	s_nop 0
	s_nop 0
	s_nop 0
	s_nop 0
	s_nop 0
	s_nop 0
	s_nop 0
	s_nop 0
	s_nop 0
	s_nop 0
	s_nop 0
	s_nop 0
	s_nop 0
	s_nop 0
	s_nop 0
	s_nop 0
	s_nop 0
	s_nop 0
	s_nop 0
	s_nop 0
	s_nop 0
	s_nop 0
	s_nop 0
	s_nop 0
	s_nop 0
	s_nop 0
	s_nop 0
	s_nop 0
	s_nop 0
	s_nop 0
	s_nop 0
	s_nop 0
	s_nop 0
	s_nop 0
	s_nop 0
	s_nop 0
	s_nop 0
	s_nop 0
	s_nop 0
	s_nop 0
	s_nop 0
	s_nop 0
	s_nop 0
	s_nop 0
	s_nop 0
	s_nop 0
	s_nop 0
	s_nop 0
	s_nop 0
	s_nop 0
	s_nop 0
	s_nop 0
	s_nop 0
	s_nop 0
	s_nop 0
	s_nop 0
	s_nop 0
	s_nop 0
	s_nop 0
	s_nop 0
	s_nop 0
	s_nop 0
	s_nop 0
	s_nop 0
	s_nop 0
	s_nop 0
	s_nop 0
	s_nop 0
	s_nop 0
	s_nop 0
	s_nop 0
	s_nop 0
	s_nop 0
	s_nop 0
	s_nop 0
	s_nop 0
	s_nop 0
	s_nop 0
	s_nop 0
	s_nop 0
	s_nop 0
	s_nop 0
	s_nop 0
	s_nop 0
	s_nop 0
	s_nop 0
	s_nop 0
	s_nop 0
	s_nop 0
	s_nop 0
	s_nop 0
	s_nop 0
	s_nop 0
	s_nop 0
	s_nop 0
	s_nop 0
	s_nop 0
	s_nop 0
	s_nop 0
	s_nop 0
	s_nop 0
	s_nop 0
	s_nop 0
	s_nop 0
	s_nop 0
	s_nop 0
	s_nop 0
	s_nop 0
	s_nop 0
	s_nop 0
	s_nop 0
	s_nop 0
	s_nop 0
	s_nop 0
	s_nop 0
	s_nop 0
	s_nop 0
	s_nop 0
	s_nop 0
	s_nop 0
	s_nop 0
	s_nop 0
	s_nop 0
	s_nop 0
	s_nop 0
	s_nop 0
	s_nop 0
	s_nop 0
	s_nop 0
	s_nop 0
	s_nop 0
	s_nop 0
	s_nop 0
	s_nop 0
	s_nop 0
	s_nop 0
	s_nop 0
	s_nop 0
	s_nop 0
	s_nop 0
	s_nop 0
	s_nop 0
	s_nop 0
	s_nop 0
	s_nop 0
	s_nop 0
	s_nop 0
	s_nop 0
	s_nop 0
	s_nop 0
	s_nop 0
	s_nop 0
	s_nop 0
	s_nop 0
	s_nop 0
	s_nop 0
	s_nop 0
	s_nop 0
	s_nop 0
	s_nop 0
	s_nop 0
	s_nop 0
	s_nop 0
	s_nop 0
	s_nop 0
	s_nop 0
	s_nop 0
	s_nop 0
	s_nop 0
	s_nop 0
	s_nop 0
	s_nop 0
	s_nop 0
	s_nop 0
	s_nop 0
	s_nop 0
	s_nop 0
	s_nop 0
	s_nop 0
	s_nop 0
	s_nop 0
	s_nop 0
	s_nop 0
	s_nop 0
	s_nop 0
	s_nop 0
	s_nop 0
	s_nop 0
	s_nop 0
	s_nop 0
	s_nop 0
	s_nop 0
	s_nop 0
	s_nop 0
	s_nop 0
	s_nop 0
	s_nop 0
	s_nop 0
	s_nop 0
	s_nop 0
	s_nop 0
	s_nop 0
	s_nop 0
	s_nop 0
	s_nop 0
	s_nop 0
	s_nop 0
	s_nop 0
	s_nop 0
	s_nop 0
	s_nop 0
	s_nop 0
	s_nop 0
	s_nop 0
	s_nop 0
	s_nop 0
	s_nop 0
	s_nop 0
	s_nop 0
	s_nop 0
	s_nop 0
	s_nop 0
	s_nop 0
	s_nop 0
	s_nop 0
	s_nop 0
	s_nop 0
	s_nop 0
	s_nop 0
	s_nop 0
	s_nop 0
	s_nop 0
	s_nop 0
	s_nop 0
	s_nop 0
	s_nop 0
	s_nop 0
	s_nop 0
	s_nop 0
	s_nop 0
	s_nop 0
	s_nop 0
	s_nop 0
	s_nop 0
	s_nop 0
	s_nop 0
	s_nop 0
	s_nop 0
	s_nop 0
	s_nop 0
	s_nop 0
	s_nop 0
	s_nop 0
	s_nop 0
	s_nop 0
	s_nop 0
	s_nop 0
	s_nop 0
	s_nop 0
	s_nop 0
	s_nop 0
	s_nop 0
	s_nop 0
	s_nop 0
	s_nop 0
	s_nop 0
	s_nop 0
	s_nop 0
	s_nop 0
	s_nop 0
; __device__ __forceinline__ void subln_store(f32x16 (&o)[4], const float* subg, bf16_t* dst  , int lane) {
;     ...
;     f32x4 sg[4][4];
; #pragma unroll
;     for (int cb = 0; cb < 4; ++cb)
; #pragma unroll
;         for (int g = 0; g < 4; ++g) sg[cb][g] = *(const f32x4*)(subg + 32 * cb + 8 * g + 4 * hi);
; __device__ __forceinline__ void attnA_unit(const P2Ctx& C, int b, int h, int qb) {
;     ...
;     if (comp == 0) {
; #pragma unroll
;         for (int cb = 0; cb < 4; ++cb)
; #pragma unroll
;             for (int r = 0; r < 16; ++r) o[cb][r] = o[cb][r] * inv - lam * X2[((qs * 4 + cb) * 16 + r) * 64 + lane];
.LaA_comp0_22:
	v_lshrrev_b32_e32 v242, 5, v219
	v_lshlrev_b32_e32 v242, 4, v242
	v_add_u32_e32 v242, 0x22a00, v242
	ds_read_b128 v[100:103], v242 offset:0
	ds_read_b128 v[104:107], v242 offset:32
	ds_read_b128 v[108:111], v242 offset:64
	ds_read_b128 v[112:115], v242 offset:96
	ds_read_b128 v[116:119], v242 offset:128
	ds_read_b128 v[120:123], v242 offset:160
	ds_read_b128 v[124:127], v242 offset:192
	ds_read_b128 v[128:131], v242 offset:224
	s_waitcnt lgkmcnt(4)
	ds_read_b128 v[132:135], v242 offset:256
	ds_read_b128 v[136:139], v242 offset:288
	ds_read_b128 v[140:143], v242 offset:320
	ds_read_b128 v[144:147], v242 offset:352
	ds_read_b128 v[148:151], v242 offset:384
	ds_read_b128 v[152:155], v242 offset:416
	ds_read_b128 v[156:159], v242 offset:448
	ds_read_b128 v[160:163], v242 offset:480
	s_waitcnt lgkmcnt(6)
	ds_read_b32 v243, v207
	s_nop 7
	s_nop 3
	v_mul_f32_e32 v4, v4, v241
	v_mul_f32_e32 v5, v5, v241
	v_mul_f32_e32 v6, v6, v241
	v_mul_f32_e32 v7, v7, v241
	v_mul_f32_e32 v8, v8, v241
	v_mul_f32_e32 v9, v9, v241
	v_mul_f32_e32 v10, v10, v241
	v_mul_f32_e32 v11, v11, v241
	v_mul_f32_e32 v12, v12, v241
	v_mul_f32_e32 v13, v13, v241
	v_mul_f32_e32 v14, v14, v241
	v_mul_f32_e32 v15, v15, v241
	v_mul_f32_e32 v16, v16, v241
	v_mul_f32_e32 v17, v17, v241
	v_mul_f32_e32 v18, v18, v241
	v_mul_f32_e32 v19, v19, v241
	v_mul_f32_e32 v20, v20, v241
	v_mul_f32_e32 v21, v21, v241
	v_mul_f32_e32 v22, v22, v241
	v_mul_f32_e32 v23, v23, v241
	v_mul_f32_e32 v24, v24, v241
	v_mul_f32_e32 v25, v25, v241
	v_mul_f32_e32 v26, v26, v241
	v_mul_f32_e32 v27, v27, v241
	v_mul_f32_e32 v28, v28, v241
	v_mul_f32_e32 v29, v29, v241
	v_mul_f32_e32 v30, v30, v241
	v_mul_f32_e32 v31, v31, v241
	v_mul_f32_e32 v32, v32, v241
	v_mul_f32_e32 v33, v33, v241
	v_mul_f32_e32 v34, v34, v241
	v_mul_f32_e32 v35, v35, v241
	v_mul_f32_e32 v36, v36, v241
	v_mul_f32_e32 v37, v37, v241
	v_mul_f32_e32 v38, v38, v241
	v_mul_f32_e32 v39, v39, v241
	v_mul_f32_e32 v40, v40, v241
	v_mul_f32_e32 v41, v41, v241
	v_mul_f32_e32 v42, v42, v241
	v_mul_f32_e32 v43, v43, v241
	v_mul_f32_e32 v44, v44, v241
	v_mul_f32_e32 v45, v45, v241
	v_mul_f32_e32 v46, v46, v241
	v_mul_f32_e32 v47, v47, v241
	v_mul_f32_e32 v48, v48, v241
	v_mul_f32_e32 v49, v49, v241
	v_mul_f32_e32 v50, v50, v241
	v_mul_f32_e32 v51, v51, v241
	v_mul_f32_e32 v52, v52, v241
	v_mul_f32_e32 v53, v53, v241
	v_mul_f32_e32 v54, v54, v241
	v_mul_f32_e32 v55, v55, v241
	v_mul_f32_e32 v56, v56, v241
	v_mul_f32_e32 v57, v57, v241
	v_mul_f32_e32 v58, v58, v241
	v_mul_f32_e32 v59, v59, v241
	v_mul_f32_e32 v60, v60, v241
	v_mul_f32_e32 v61, v61, v241
	v_mul_f32_e32 v62, v62, v241
	v_mul_f32_e32 v63, v63, v241
	v_mul_f32_e32 v64, v64, v241
	v_mul_f32_e32 v65, v65, v241
	v_mul_f32_e32 v66, v66, v241
	v_mul_f32_e32 v67, v67, v241
	s_waitcnt lgkmcnt(0)
	s_barrier
	ds_read2st64_b32 v[164:165], v2 offset0:0 offset1:1
	ds_read2st64_b32 v[166:167], v2 offset0:2 offset1:3
	ds_read2st64_b32 v[168:169], v2 offset0:4 offset1:5
	ds_read2st64_b32 v[170:171], v2 offset0:6 offset1:7
	ds_read2st64_b32 v[172:173], v2 offset0:8 offset1:9
	ds_read2st64_b32 v[174:175], v2 offset0:10 offset1:11
	ds_read2st64_b32 v[176:177], v2 offset0:12 offset1:13
	ds_read2st64_b32 v[178:179], v2 offset0:14 offset1:15
	ds_read2st64_b32 v[180:181], v2 offset0:16 offset1:17
	ds_read2st64_b32 v[182:183], v2 offset0:18 offset1:19
	ds_read2st64_b32 v[184:185], v2 offset0:20 offset1:21
	ds_read2st64_b32 v[186:187], v2 offset0:22 offset1:23
	ds_read2st64_b32 v[188:189], v2 offset0:24 offset1:25
	ds_read2st64_b32 v[190:191], v2 offset0:26 offset1:27
	ds_read2st64_b32 v[192:193], v2 offset0:28 offset1:29
	s_waitcnt lgkmcnt(8)
	ds_read2st64_b32 v[194:195], v2 offset0:30 offset1:31
	ds_read2st64_b32 v[68:69], v2 offset0:32 offset1:33
	ds_read2st64_b32 v[70:71], v2 offset0:34 offset1:35
	ds_read2st64_b32 v[72:73], v2 offset0:36 offset1:37
	ds_read2st64_b32 v[74:75], v2 offset0:38 offset1:39
	ds_read2st64_b32 v[76:77], v2 offset0:40 offset1:41
	ds_read2st64_b32 v[78:79], v2 offset0:42 offset1:43
	ds_read2st64_b32 v[80:81], v2 offset0:44 offset1:45
	ds_read2st64_b32 v[82:83], v2 offset0:46 offset1:47
	ds_read2st64_b32 v[84:85], v2 offset0:48 offset1:49
	ds_read2st64_b32 v[86:87], v2 offset0:50 offset1:51
	ds_read2st64_b32 v[88:89], v2 offset0:52 offset1:53
	ds_read2st64_b32 v[90:91], v2 offset0:54 offset1:55
	ds_read2st64_b32 v[92:93], v2 offset0:56 offset1:57
	ds_read2st64_b32 v[94:95], v2 offset0:58 offset1:59
	ds_read2st64_b32 v[96:97], v2 offset0:60 offset1:61
	ds_read2st64_b32 v[98:99], v2 offset0:62 offset1:63
	s_waitcnt lgkmcnt(0)
; __device__ __forceinline__ void subln_store(f32x16 (&o)[4], const float* subg, bf16_t* dst  , int lane) {
;     const int hi = lane >> 5;
;     float ss = 0.f;
; #pragma unroll
;     for (int cb = 0; cb < 4; ++cb)
; #pragma unroll
;         for (int r = 0; r < 16; ++r) ss += o[cb][r] * o[cb][r];
;     ss += __shfl_xor(ss, 32);
;     const float rstd = (1.0f - LAMBDA_INIT) / sqrtf(ss * (1.0f / 128.0f) + EPS);
; __device__ __forceinline__ void attnA_unit(const P2Ctx& C, int b, int h, int qb) {
;     ...
;             for (int r = 0; r < 16; ++r) o[cb][r] = o[cb][r] * inv - lam * X2[((qs * 4 + cb) * 16 + r) * 64 + lane];
;         subln_store(o, C.a->in[I_SUBG], C.AO + qrow * DM + h * 128, lane);
	v_fma_f32 v4, -v243, v164, v4
	v_fma_f32 v5, -v243, v165, v5
	v_fma_f32 v6, -v243, v166, v6
	v_fma_f32 v7, -v243, v167, v7
	v_fma_f32 v8, -v243, v168, v8
	v_fma_f32 v9, -v243, v169, v9
	v_fma_f32 v10, -v243, v170, v10
	v_fma_f32 v11, -v243, v171, v11
	v_fma_f32 v12, -v243, v172, v12
	v_fma_f32 v13, -v243, v173, v13
	v_fma_f32 v14, -v243, v174, v14
	v_fma_f32 v15, -v243, v175, v15
	v_fma_f32 v16, -v243, v176, v16
	v_fma_f32 v17, -v243, v177, v17
	v_fma_f32 v18, -v243, v178, v18
	v_fma_f32 v19, -v243, v179, v19
	v_fma_f32 v20, -v243, v180, v20
	v_fma_f32 v21, -v243, v181, v21
	v_fma_f32 v22, -v243, v182, v22
	v_fma_f32 v23, -v243, v183, v23
	v_fma_f32 v24, -v243, v184, v24
	v_fma_f32 v25, -v243, v185, v25
	v_fma_f32 v26, -v243, v186, v26
	v_fma_f32 v27, -v243, v187, v27
	v_fma_f32 v28, -v243, v188, v28
	v_fma_f32 v29, -v243, v189, v29
	v_fma_f32 v30, -v243, v190, v30
	v_fma_f32 v31, -v243, v191, v31
	v_fma_f32 v32, -v243, v192, v32
	v_fma_f32 v33, -v243, v193, v33
	v_fma_f32 v34, -v243, v194, v34
	v_fma_f32 v35, -v243, v195, v35
	v_fma_f32 v36, -v243, v68, v36
	v_fma_f32 v37, -v243, v69, v37
	v_fma_f32 v38, -v243, v70, v38
	v_fma_f32 v39, -v243, v71, v39
	v_fma_f32 v40, -v243, v72, v40
	v_fma_f32 v41, -v243, v73, v41
	v_fma_f32 v42, -v243, v74, v42
	v_fma_f32 v43, -v243, v75, v43
	v_fma_f32 v44, -v243, v76, v44
	v_fma_f32 v45, -v243, v77, v45
	v_fma_f32 v46, -v243, v78, v46
	v_fma_f32 v47, -v243, v79, v47
	v_fma_f32 v48, -v243, v80, v48
	v_fma_f32 v49, -v243, v81, v49
	v_fma_f32 v50, -v243, v82, v50
	v_fma_f32 v51, -v243, v83, v51
	v_fma_f32 v52, -v243, v84, v52
	v_fma_f32 v53, -v243, v85, v53
	v_fma_f32 v54, -v243, v86, v54
	v_fma_f32 v55, -v243, v87, v55
	v_fma_f32 v56, -v243, v88, v56
	v_fma_f32 v57, -v243, v89, v57
	v_fma_f32 v58, -v243, v90, v58
	v_fma_f32 v59, -v243, v91, v59
	v_fma_f32 v60, -v243, v92, v60
	v_fma_f32 v61, -v243, v93, v61
	v_fma_f32 v62, -v243, v94, v62
	v_fma_f32 v63, -v243, v95, v63
	v_fma_f32 v64, -v243, v96, v64
	v_fma_f32 v65, -v243, v97, v65
	v_fma_f32 v66, -v243, v98, v66
	v_fma_f32 v67, -v243, v99, v67
	v_mul_f32_e32 v245, v4, v4
	v_fmac_f32_e32 v245, v5, v5
	v_fmac_f32_e32 v245, v6, v6
	v_fmac_f32_e32 v245, v7, v7
	v_fmac_f32_e32 v245, v8, v8
	v_fmac_f32_e32 v245, v9, v9
	v_fmac_f32_e32 v245, v10, v10
	v_fmac_f32_e32 v245, v11, v11
	v_fmac_f32_e32 v245, v12, v12
	v_fmac_f32_e32 v245, v13, v13
	v_fmac_f32_e32 v245, v14, v14
	v_fmac_f32_e32 v245, v15, v15
	v_fmac_f32_e32 v245, v16, v16
	v_fmac_f32_e32 v245, v17, v17
	v_fmac_f32_e32 v245, v18, v18
	v_fmac_f32_e32 v245, v19, v19
	v_fmac_f32_e32 v245, v20, v20
	v_fmac_f32_e32 v245, v21, v21
	v_fmac_f32_e32 v245, v22, v22
	v_fmac_f32_e32 v245, v23, v23
	v_fmac_f32_e32 v245, v24, v24
	v_fmac_f32_e32 v245, v25, v25
	v_fmac_f32_e32 v245, v26, v26
	v_fmac_f32_e32 v245, v27, v27
	v_fmac_f32_e32 v245, v28, v28
	v_fmac_f32_e32 v245, v29, v29
	v_fmac_f32_e32 v245, v30, v30
	v_fmac_f32_e32 v245, v31, v31
	v_fmac_f32_e32 v245, v32, v32
	v_fmac_f32_e32 v245, v33, v33
	v_fmac_f32_e32 v245, v34, v34
	v_fmac_f32_e32 v245, v35, v35
	v_fmac_f32_e32 v245, v36, v36
	v_fmac_f32_e32 v245, v37, v37
	v_fmac_f32_e32 v245, v38, v38
	v_fmac_f32_e32 v245, v39, v39
	v_fmac_f32_e32 v245, v40, v40
	v_fmac_f32_e32 v245, v41, v41
	v_fmac_f32_e32 v245, v42, v42
	v_fmac_f32_e32 v245, v43, v43
	v_fmac_f32_e32 v245, v44, v44
	v_fmac_f32_e32 v245, v45, v45
	v_fmac_f32_e32 v245, v46, v46
	v_fmac_f32_e32 v245, v47, v47
	v_fmac_f32_e32 v245, v48, v48
	v_fmac_f32_e32 v245, v49, v49
	v_fmac_f32_e32 v245, v50, v50
	v_fmac_f32_e32 v245, v51, v51
	v_fmac_f32_e32 v245, v52, v52
	v_fmac_f32_e32 v245, v53, v53
	v_fmac_f32_e32 v245, v54, v54
	v_fmac_f32_e32 v245, v55, v55
	v_fmac_f32_e32 v245, v56, v56
	v_fmac_f32_e32 v245, v57, v57
	v_fmac_f32_e32 v245, v58, v58
	v_fmac_f32_e32 v245, v59, v59
	v_fmac_f32_e32 v245, v60, v60
	v_fmac_f32_e32 v245, v61, v61
	v_fmac_f32_e32 v245, v62, v62
	v_fmac_f32_e32 v245, v63, v63
	v_fmac_f32_e32 v245, v64, v64
	v_fmac_f32_e32 v245, v65, v65
	v_fmac_f32_e32 v245, v66, v66
	v_fmac_f32_e32 v245, v67, v67
	v_mov_b32_e32 v246, v245
	s_nop 1
	v_permlane32_swap_b32 v246, v245
	v_add_f32_e32 v245, v246, v245
	v_mov_b32_e32 v246, 0x3c000000
	v_fmaak_f32 v245, v245, v246, 0x358637bd
	v_rsq_f32_e32 v245, v245
	s_nop 0
	v_mul_f32_e32 v245, 0x3f4ccccd, v245
	s_lshl_b32 s6, s11, 11
	s_add_i32 s6, s6, s15
	s_lshl_b32 s6, s6, 11
	s_lshl_b32 s7, s81, 1
	s_add_i32 s6, s6, s7
	s_add_u32 s20, s70, s6
	s_addc_u32 s21, s71, 0
	v_and_b32_e32 v242, 31, v219
	v_lshlrev_b32_e32 v242, 11, v242
	v_lshrrev_b32_e32 v243, 5, v219
	v_lshl_add_u32 v242, v243, 3, v242
	s_waitcnt vmcnt(0)
; __device__ __forceinline__ unsigned pk_bf16(float lo, float hi) { f32x2 v = {lo, hi}; bf16x2_t b = __builtin_convertvector(v, bf16x2_t); return __builtin_bit_cast(unsigned, b); }
; __device__ __forceinline__ void subln_store(f32x16 (&o)[4], const float* subg, bf16_t* dst  , int lane) {
;     ...
;     for (int cb = 0; cb < 4; ++cb)
; #pragma unroll
;         for (int g = 0; g < 4; ++g) { const int dv0 = 32 * cb + 8 * g + 4 * hi; const f32x4 s4 = sg[cb][g];
;             u32x2 w; w.x = pk_bf16(o[cb][4 * g + 0] * rstd * s4[0], o[cb][4 * g + 1] * rstd * s4[1]); w.y = pk_bf16(o[cb][4 * g + 2] * rstd * s4[2], o[cb][4 * g + 3] * rstd * s4[3]);
;             *(u32x2*)(dst + dv0) = w; }
	v_mul_f32_e32 v4, v4, v245
	v_mul_f32_e32 v5, v5, v245
	v_mul_f32_e32 v6, v6, v245
	v_mul_f32_e32 v7, v7, v245
	v_mul_f32_e32 v4, v4, v100
	v_mul_f32_e32 v5, v5, v101
	v_mul_f32_e32 v6, v6, v102
	v_mul_f32_e32 v7, v7, v103
	v_cvt_pk_bf16_f32 v68, v4, v5
	v_cvt_pk_bf16_f32 v69, v6, v7
	global_store_dwordx2 v242, v[68:69], s[20:21] offset:0
	v_mul_f32_e32 v8, v8, v245
	v_mul_f32_e32 v9, v9, v245
	v_mul_f32_e32 v10, v10, v245
	v_mul_f32_e32 v11, v11, v245
	v_mul_f32_e32 v8, v8, v104
	v_mul_f32_e32 v9, v9, v105
	v_mul_f32_e32 v10, v10, v106
	v_mul_f32_e32 v11, v11, v107
	v_cvt_pk_bf16_f32 v70, v8, v9
	v_cvt_pk_bf16_f32 v71, v10, v11
	global_store_dwordx2 v242, v[70:71], s[20:21] offset:16
	v_mul_f32_e32 v12, v12, v245
	v_mul_f32_e32 v13, v13, v245
	v_mul_f32_e32 v14, v14, v245
	v_mul_f32_e32 v15, v15, v245
	v_mul_f32_e32 v12, v12, v108
	v_mul_f32_e32 v13, v13, v109
	v_mul_f32_e32 v14, v14, v110
	v_mul_f32_e32 v15, v15, v111
	v_cvt_pk_bf16_f32 v68, v12, v13
	v_cvt_pk_bf16_f32 v69, v14, v15
	global_store_dwordx2 v242, v[68:69], s[20:21] offset:32
	v_mul_f32_e32 v16, v16, v245
	v_mul_f32_e32 v17, v17, v245
	v_mul_f32_e32 v18, v18, v245
	v_mul_f32_e32 v19, v19, v245
	v_mul_f32_e32 v16, v16, v112
	v_mul_f32_e32 v17, v17, v113
	v_mul_f32_e32 v18, v18, v114
	v_mul_f32_e32 v19, v19, v115
	v_cvt_pk_bf16_f32 v70, v16, v17
	v_cvt_pk_bf16_f32 v71, v18, v19
	global_store_dwordx2 v242, v[70:71], s[20:21] offset:48
	v_mul_f32_e32 v20, v20, v245
	v_mul_f32_e32 v21, v21, v245
	v_mul_f32_e32 v22, v22, v245
	v_mul_f32_e32 v23, v23, v245
	v_mul_f32_e32 v20, v20, v116
	v_mul_f32_e32 v21, v21, v117
	v_mul_f32_e32 v22, v22, v118
	v_mul_f32_e32 v23, v23, v119
	v_cvt_pk_bf16_f32 v68, v20, v21
	v_cvt_pk_bf16_f32 v69, v22, v23
	global_store_dwordx2 v242, v[68:69], s[20:21] offset:64
	v_mul_f32_e32 v24, v24, v245
	v_mul_f32_e32 v25, v25, v245
	v_mul_f32_e32 v26, v26, v245
	v_mul_f32_e32 v27, v27, v245
	v_mul_f32_e32 v24, v24, v120
	v_mul_f32_e32 v25, v25, v121
	v_mul_f32_e32 v26, v26, v122
	v_mul_f32_e32 v27, v27, v123
	v_cvt_pk_bf16_f32 v70, v24, v25
	v_cvt_pk_bf16_f32 v71, v26, v27
	global_store_dwordx2 v242, v[70:71], s[20:21] offset:80
	v_mul_f32_e32 v28, v28, v245
	v_mul_f32_e32 v29, v29, v245
	v_mul_f32_e32 v30, v30, v245
	v_mul_f32_e32 v31, v31, v245
	v_mul_f32_e32 v28, v28, v124
	v_mul_f32_e32 v29, v29, v125
	v_mul_f32_e32 v30, v30, v126
	v_mul_f32_e32 v31, v31, v127
	v_cvt_pk_bf16_f32 v68, v28, v29
	v_cvt_pk_bf16_f32 v69, v30, v31
	global_store_dwordx2 v242, v[68:69], s[20:21] offset:96
	v_mul_f32_e32 v32, v32, v245
	v_mul_f32_e32 v33, v33, v245
	v_mul_f32_e32 v34, v34, v245
	v_mul_f32_e32 v35, v35, v245
	v_mul_f32_e32 v32, v32, v128
	v_mul_f32_e32 v33, v33, v129
	v_mul_f32_e32 v34, v34, v130
	v_mul_f32_e32 v35, v35, v131
	v_cvt_pk_bf16_f32 v70, v32, v33
	v_cvt_pk_bf16_f32 v71, v34, v35
	global_store_dwordx2 v242, v[70:71], s[20:21] offset:112
	v_mul_f32_e32 v36, v36, v245
	v_mul_f32_e32 v37, v37, v245
	v_mul_f32_e32 v38, v38, v245
	v_mul_f32_e32 v39, v39, v245
	v_mul_f32_e32 v36, v36, v132
	v_mul_f32_e32 v37, v37, v133
	v_mul_f32_e32 v38, v38, v134
	v_mul_f32_e32 v39, v39, v135
	v_cvt_pk_bf16_f32 v68, v36, v37
	v_cvt_pk_bf16_f32 v69, v38, v39
	global_store_dwordx2 v242, v[68:69], s[20:21] offset:128
	v_mul_f32_e32 v40, v40, v245
	v_mul_f32_e32 v41, v41, v245
	v_mul_f32_e32 v42, v42, v245
	v_mul_f32_e32 v43, v43, v245
	v_mul_f32_e32 v40, v40, v136
	v_mul_f32_e32 v41, v41, v137
	v_mul_f32_e32 v42, v42, v138
	v_mul_f32_e32 v43, v43, v139
	v_cvt_pk_bf16_f32 v70, v40, v41
	v_cvt_pk_bf16_f32 v71, v42, v43
	global_store_dwordx2 v242, v[70:71], s[20:21] offset:144
	v_mul_f32_e32 v44, v44, v245
	v_mul_f32_e32 v45, v45, v245
	v_mul_f32_e32 v46, v46, v245
	v_mul_f32_e32 v47, v47, v245
	v_mul_f32_e32 v44, v44, v140
	v_mul_f32_e32 v45, v45, v141
	v_mul_f32_e32 v46, v46, v142
	v_mul_f32_e32 v47, v47, v143
	v_cvt_pk_bf16_f32 v68, v44, v45
	v_cvt_pk_bf16_f32 v69, v46, v47
	global_store_dwordx2 v242, v[68:69], s[20:21] offset:160
	v_mul_f32_e32 v48, v48, v245
	v_mul_f32_e32 v49, v49, v245
	v_mul_f32_e32 v50, v50, v245
	v_mul_f32_e32 v51, v51, v245
	v_mul_f32_e32 v48, v48, v144
	v_mul_f32_e32 v49, v49, v145
	v_mul_f32_e32 v50, v50, v146
	v_mul_f32_e32 v51, v51, v147
	v_cvt_pk_bf16_f32 v70, v48, v49
	v_cvt_pk_bf16_f32 v71, v50, v51
	global_store_dwordx2 v242, v[70:71], s[20:21] offset:176
	v_mul_f32_e32 v52, v52, v245
	v_mul_f32_e32 v53, v53, v245
	v_mul_f32_e32 v54, v54, v245
	v_mul_f32_e32 v55, v55, v245
	v_mul_f32_e32 v52, v52, v148
	v_mul_f32_e32 v53, v53, v149
	v_mul_f32_e32 v54, v54, v150
	v_mul_f32_e32 v55, v55, v151
	v_cvt_pk_bf16_f32 v68, v52, v53
	v_cvt_pk_bf16_f32 v69, v54, v55
	global_store_dwordx2 v242, v[68:69], s[20:21] offset:192
	v_mul_f32_e32 v56, v56, v245
	v_mul_f32_e32 v57, v57, v245
	v_mul_f32_e32 v58, v58, v245
	v_mul_f32_e32 v59, v59, v245
	v_mul_f32_e32 v56, v56, v152
	v_mul_f32_e32 v57, v57, v153
	v_mul_f32_e32 v58, v58, v154
	v_mul_f32_e32 v59, v59, v155
	v_cvt_pk_bf16_f32 v70, v56, v57
	v_cvt_pk_bf16_f32 v71, v58, v59
	global_store_dwordx2 v242, v[70:71], s[20:21] offset:208
	v_mul_f32_e32 v60, v60, v245
	v_mul_f32_e32 v61, v61, v245
	v_mul_f32_e32 v62, v62, v245
	v_mul_f32_e32 v63, v63, v245
	v_mul_f32_e32 v60, v60, v156
	v_mul_f32_e32 v61, v61, v157
	v_mul_f32_e32 v62, v62, v158
	v_mul_f32_e32 v63, v63, v159
	v_cvt_pk_bf16_f32 v68, v60, v61
	v_cvt_pk_bf16_f32 v69, v62, v63
	global_store_dwordx2 v242, v[68:69], s[20:21] offset:224
	v_mul_f32_e32 v64, v64, v245
	v_mul_f32_e32 v65, v65, v245
	v_mul_f32_e32 v66, v66, v245
	v_mul_f32_e32 v67, v67, v245
	v_mul_f32_e32 v64, v64, v160
	v_mul_f32_e32 v65, v65, v161
	v_mul_f32_e32 v66, v66, v162
	v_mul_f32_e32 v67, v67, v163
	v_cvt_pk_bf16_f32 v70, v64, v65
	v_cvt_pk_bf16_f32 v71, v66, v67
	global_store_dwordx2 v242, v[70:71], s[20:21] offset:240
